# grid barrier: L1 invalidate (acquire) issued right after the arrival atomic so it overlaps the wait/write-back, instead of after the release
# speedup vs baseline: 1.0123x; 1.0066x over previous
.LBB0_179:
	s_or_b64 exec, exec, s[8:9]
	v_cvt_f32_u32_e32 v4, v2
	s_waitcnt vmcnt(0)
	v_readfirstlane_b32 s6, v3
	buffer_inv sc1
	v_sub_u32_e32 v3, 0, v2
	v_rcp_iflag_f32_e32 v4, v4
	v_add_u32_e32 v5, s6, v1
	v_mul_f32_e32 v4, 0x4f7ffffe, v4
	v_cvt_u32_f32_e32 v4, v4
	v_mul_lo_u32 v1, v3, v4
	v_mul_hi_u32 v1, v4, v1
	v_add_u32_e32 v1, v4, v1
	v_mul_hi_u32 v1, v5, v1
	v_mul_lo_u32 v3, v1, v2
	v_sub_u32_e32 v3, v5, v3
	v_add_u32_e32 v4, 1, v1
	v_cmp_ge_u32_e32 vcc, v3, v2
	s_nop 1
	v_cndmask_b32_e32 v1, v1, v4, vcc
	v_sub_u32_e32 v4, v3, v2
	v_cndmask_b32_e32 v3, v3, v4, vcc
	v_add_u32_e32 v4, 1, v1
	v_cmp_ge_u32_e32 vcc, v3, v2
	v_add_u32_e32 v3, 1, v5
	s_nop 0
	v_cndmask_b32_e32 v1, v1, v4, vcc
	v_mul_lo_u32 v4, v2, v1
	v_add_u32_e32 v2, v4, v2
	v_cmp_ne_u32_e32 vcc, v3, v2
	s_and_saveexec_b64 s[6:7], vcc
	s_xor_b64 s[6:7], exec, s[6:7]
	s_cbranch_execz .LBB0_193
	s_waitcnt lgkmcnt(0)
	v_mov_b32_e32 v0, 0x2000
	global_load_dword v0, v0, s[4:5] offset:1024 sc1
	s_add_u32 s12, s4, 0x2400
	s_addc_u32 s13, s5, 0
	s_waitcnt vmcnt(0)
	v_cmp_eq_u32_e32 vcc, v0, v1
	s_and_saveexec_b64 s[8:9], vcc
	s_cbranch_execz .LBB0_192
	s_add_u32 s10, s22, 0x2cb8200
	s_addc_u32 s11, s23, 0
	s_mov_b32 s30, 1
	s_mov_b64 s[14:15], 0
	v_mov_b32_e32 v0, 0
	s_branch .LBB0_183

.LBB0_192:
	s_or_b64 exec, exec, s[8:9]
	s_waitcnt vmcnt(0)
	s_waitcnt vmcnt(0)

.LBB0_210:
	s_or_b64 exec, exec, s[6:7]
	s_mov_b64 s[6:7], exec
	v_mbcnt_lo_u32_b32 v0, s6, 0
	v_mbcnt_hi_u32_b32 v0, s7, v0
	v_cmp_eq_u32_e32 vcc, 0, v0
	s_waitcnt vmcnt(0)
	s_and_saveexec_b64 s[8:9], vcc
	s_cbranch_execz .LBB0_212
	s_bcnt1_i32_b64 s6, s[6:7]
	v_mov_b32_e32 v0, 0x2000
	v_mov_b32_e32 v1, s6
	global_atomic_add v0, v1, s[4:5] offset:1024

.LBB0_964:
	s_or_b64 exec, exec, s[10:11]
	v_cvt_f32_u32_e32 v4, v2
	s_waitcnt vmcnt(0)
	v_readfirstlane_b32 s8, v3
	buffer_inv sc1
	v_sub_u32_e32 v3, 0, v2
	v_rcp_iflag_f32_e32 v4, v4
	v_add_u32_e32 v5, s8, v1
	v_mul_f32_e32 v4, 0x4f7ffffe, v4
	v_cvt_u32_f32_e32 v4, v4
	v_mul_lo_u32 v1, v3, v4
	v_mul_hi_u32 v1, v4, v1
	v_add_u32_e32 v1, v4, v1
	v_mul_hi_u32 v1, v5, v1
	v_mul_lo_u32 v3, v1, v2
	v_sub_u32_e32 v3, v5, v3
	v_add_u32_e32 v4, 1, v1
	v_cmp_ge_u32_e32 vcc, v3, v2
	s_nop 1
	v_cndmask_b32_e32 v1, v1, v4, vcc
	v_sub_u32_e32 v4, v3, v2
	v_cndmask_b32_e32 v3, v3, v4, vcc
	v_add_u32_e32 v4, 1, v1
	v_cmp_ge_u32_e32 vcc, v3, v2
	v_add_u32_e32 v3, 1, v5
	s_nop 0
	v_cndmask_b32_e32 v1, v1, v4, vcc
	v_mul_lo_u32 v4, v2, v1
	v_add_u32_e32 v2, v4, v2
	v_cmp_ne_u32_e32 vcc, v3, v2
	s_and_saveexec_b64 s[8:9], vcc
	s_xor_b64 s[8:9], exec, s[8:9]
	s_cbranch_execz .LBB0_978
	s_waitcnt lgkmcnt(0)
	v_mov_b32_e32 v0, 0x2000
	global_load_dword v0, v0, s[6:7] offset:1024 sc1
	s_add_u32 s14, s6, 0x2400
	s_addc_u32 s15, s7, 0
	s_waitcnt vmcnt(0)
	v_cmp_eq_u32_e32 vcc, v0, v1
	s_and_saveexec_b64 s[10:11], vcc
	s_cbranch_execz .LBB0_977
	s_add_u32 s12, s22, 0x2cb8200
	s_addc_u32 s13, s23, 0
	s_mov_b32 s38, 1
	s_mov_b64 s[16:17], 0
	v_mov_b32_e32 v0, 0
	s_branch .LBB0_968

.LBB0_977:
	s_or_b64 exec, exec, s[10:11]
	s_waitcnt vmcnt(0)
	s_waitcnt vmcnt(0)

.LBB0_995:
	s_or_b64 exec, exec, s[8:9]
	s_mov_b64 s[8:9], exec
	v_mbcnt_lo_u32_b32 v0, s8, 0
	v_mbcnt_hi_u32_b32 v0, s9, v0
	v_cmp_eq_u32_e32 vcc, 0, v0
	s_waitcnt vmcnt(0)
	s_and_saveexec_b64 s[10:11], vcc
	s_cbranch_execz .LBB0_997
	s_bcnt1_i32_b64 s8, s[8:9]
	v_mov_b32_e32 v0, 0x2000
	v_mov_b32_e32 v1, s8
	global_atomic_add v0, v1, s[6:7] offset:1024

.LBB0_1347:
	s_or_b64 exec, exec, s[8:9]
	v_cvt_f32_u32_e32 v4, v2
	s_waitcnt vmcnt(0)
	v_readfirstlane_b32 s6, v3
	buffer_inv sc1
	v_sub_u32_e32 v3, 0, v2
	v_rcp_iflag_f32_e32 v4, v4
	v_add_u32_e32 v5, s6, v1
	v_mul_f32_e32 v4, 0x4f7ffffe, v4
	v_cvt_u32_f32_e32 v4, v4
	v_mul_lo_u32 v1, v3, v4
	v_mul_hi_u32 v1, v4, v1
	v_add_u32_e32 v1, v4, v1
	v_mul_hi_u32 v1, v5, v1
	v_mul_lo_u32 v3, v1, v2
	v_sub_u32_e32 v3, v5, v3
	v_add_u32_e32 v4, 1, v1
	v_cmp_ge_u32_e32 vcc, v3, v2
	s_nop 1
	v_cndmask_b32_e32 v1, v1, v4, vcc
	v_sub_u32_e32 v4, v3, v2
	v_cndmask_b32_e32 v3, v3, v4, vcc
	v_add_u32_e32 v4, 1, v1
	v_cmp_ge_u32_e32 vcc, v3, v2
	v_add_u32_e32 v3, 1, v5
	s_nop 0
	v_cndmask_b32_e32 v1, v1, v4, vcc
	v_mul_lo_u32 v4, v2, v1
	v_add_u32_e32 v2, v4, v2
	v_cmp_ne_u32_e32 vcc, v3, v2
	s_and_saveexec_b64 s[6:7], vcc
	s_xor_b64 s[6:7], exec, s[6:7]
	s_cbranch_execz .LBB0_1361
	s_waitcnt lgkmcnt(0)
	v_mov_b32_e32 v0, 0x2000
	global_load_dword v0, v0, s[4:5] offset:1024 sc1
	s_add_u32 s12, s4, 0x2400
	s_addc_u32 s13, s5, 0
	s_waitcnt vmcnt(0)
	v_cmp_eq_u32_e32 vcc, v0, v1
	s_and_saveexec_b64 s[8:9], vcc
	s_cbranch_execz .LBB0_1360
	s_add_u32 s10, s22, 0x2cb8200
	s_addc_u32 s11, s23, 0
	s_mov_b32 s21, 1
	s_mov_b64 s[14:15], 0
	v_mov_b32_e32 v0, 0
	s_branch .LBB0_1351
